# baseline (speedup 1.0000x reference)
; __device__ __forceinline__ unsigned xb_ld(unsigned* p)              { return __hip_atomic_load(p, __ATOMIC_RELAXED, __HIP_MEMORY_SCOPE_AGENT); }
; __device__ __forceinline__ unsigned xb_add(unsigned* p, unsigned v) { return __hip_atomic_fetch_add(p, v, __ATOMIC_RELAXED, __HIP_MEMORY_SCOPE_AGENT); }
; #define XB_SPIN(cond, bar) do { unsigned _sp = 0; while (cond) { __builtin_amdgcn_s_sleep(1); \
;     if ((++_sp & 255u) == 0u) { if (xb_ld(&(bar)[XB_TMO])) break; if (_sp > XB_SPIN_CAP) { atomicAdd(&(bar)[XB_TMO], 1u); break; } } } } while (0)
; __device__ __forceinline__ void xcd_barrier(const XcdBarrier& b) {
;     ...
;     const unsigned old = xb_add(&bar[XB_XSUB(b.x)], 1u);
;     const unsigned gen = old / nloc;
;     if (old + 1u == (gen + 1u) * nloc) {
;       __builtin_amdgcn_fence(__ATOMIC_RELEASE, "agent");
;       asm volatile("s_waitcnt vmcnt(0)" ::: "memory");
;       const unsigned og = xb_add(&bar[XB_TOP], 1u);
;       const unsigned tg = og / nx;
;       if (og + 1u == (tg + 1u) * nx) xb_add(&bar[XB_TOPGEN], 1u);
;       else XB_SPIN(xb_ld(&bar[XB_TOPGEN]) == tg, bar);
.LBB0_859:
	s_or_b64 exec, exec, s[40:41]
	s_waitcnt vmcnt(0)
	v_readfirstlane_b32 s4, v2
	v_cvt_f32_u32_e32 v2, v0
	v_sub_u32_e32 v3, 0, v0
	v_add_u32_e32 v1, s4, v1
	v_readlane_b32 s4, v251, 30
	v_rcp_iflag_f32_e32 v2, v2
	v_readlane_b32 s5, v251, 31
	s_mov_b64 s[40:41], 0
	v_mul_f32_e32 v2, 0x4f7ffffe, v2
	v_cvt_u32_f32_e32 v2, v2
	v_mul_lo_u32 v3, v3, v2
	v_mul_hi_u32 v3, v2, v3
	v_add_u32_e32 v2, v2, v3
	v_mul_hi_u32 v2, v1, v2
	v_mul_lo_u32 v3, v2, v0
	v_sub_u32_e32 v3, v1, v3
	v_cmp_ge_u32_e32 vcc, v3, v0
	v_add_u32_e32 v4, 1, v2
	v_add_u32_e32 v1, 1, v1
	v_cndmask_b32_e32 v2, v2, v4, vcc
	v_sub_u32_e32 v4, v3, v0
	v_cndmask_b32_e32 v3, v3, v4, vcc
	v_cmp_ge_u32_e32 vcc, v3, v0
	v_add_u32_e32 v3, 1, v2
	s_nop 0
	v_cndmask_b32_e32 v2, v2, v3, vcc
	v_mul_lo_u32 v3, v0, v2
	v_add_u32_e32 v0, v3, v0
	v_mov_b32_e32 v4, v0
	v_cmp_ne_u32_e32 vcc, v1, v0
	v_mov_b64_e32 v[0:1], s[4:5]
	s_and_saveexec_b64 s[38:39], vcc
	s_cbranch_execz .LBB0_871
	v_readlane_b32 s4, v251, 28
	v_readlane_b32 s5, v251, 29
	s_mov_b64 s[42:43], 0
	s_nop 3
	global_load_dword v0, v177, s[4:5] sc1
	s_waitcnt vmcnt(0)
	v_cmp_lt_u32_e32 vcc, v0, v4
	s_and_saveexec_b64 s[40:41], vcc
	s_cbranch_execz .LBB0_870
	s_mov_b32 s11, 1
	s_branch .LBB0_863

; __device__ __forceinline__ unsigned xb_ld(unsigned* p)              { return __hip_atomic_load(p, __ATOMIC_RELAXED, __HIP_MEMORY_SCOPE_AGENT); }
; __device__ __forceinline__ unsigned xb_add(unsigned* p, unsigned v) { return __hip_atomic_fetch_add(p, v, __ATOMIC_RELAXED, __HIP_MEMORY_SCOPE_AGENT); }
; #define XB_SPIN(cond, bar) do { unsigned _sp = 0; while (cond) { __builtin_amdgcn_s_sleep(1); \
;     if ((++_sp & 255u) == 0u) { if (xb_ld(&(bar)[XB_TMO])) break; if (_sp > XB_SPIN_CAP) { atomicAdd(&(bar)[XB_TMO], 1u); break; } } } } while (0)
; __device__ __forceinline__ void xcd_barrier(const XcdBarrier& b) {
;     ...
;       const unsigned og = xb_add(&bar[XB_TOP], 1u);
;       const unsigned tg = og / nx;
;       if (og + 1u == (tg + 1u) * nx) xb_add(&bar[XB_TOPGEN], 1u);
;       else XB_SPIN(xb_ld(&bar[XB_TOPGEN]) == tg, bar);
.LBB0_867:
	v_readlane_b32 s4, v251, 28
	v_readlane_b32 s5, v251, 29
	s_add_i32 s11, s11, 1
	s_mov_b64 s[90:91], -1
	s_nop 2
	global_load_dword v0, v177, s[4:5] sc1
	s_waitcnt vmcnt(0)
	v_cmp_ge_u32_e32 vcc, v0, v4
	s_orn2_b64 s[88:89], vcc, exec
	s_branch .LBB0_862
.LBB0_868:
	s_cmp_lt_u32 s11, 0x2001
	s_mov_b64 s[90:91], 0
	s_cselect_b64 vcc, -1, 0
	s_and_b64 vcc, exec, vcc
	s_cbranch_vccz .LBB0_862
	s_branch .LBB0_867

; __device__ __forceinline__ unsigned xb_ld(unsigned* p)              { return __hip_atomic_load(p, __ATOMIC_RELAXED, __HIP_MEMORY_SCOPE_AGENT); }
; __device__ __forceinline__ unsigned xb_add(unsigned* p, unsigned v) { return __hip_atomic_fetch_add(p, v, __ATOMIC_RELAXED, __HIP_MEMORY_SCOPE_AGENT); }
; #define XB_SPIN(cond, bar) do { unsigned _sp = 0; while (cond) { __builtin_amdgcn_s_sleep(1); \
;     if ((++_sp & 255u) == 0u) { if (xb_ld(&(bar)[XB_TMO])) break; if (_sp > XB_SPIN_CAP) { atomicAdd(&(bar)[XB_TMO], 1u); break; } } } } while (0)
; __device__ __forceinline__ void xcd_barrier(const XcdBarrier& b) {
;     ...
;     const unsigned old = xb_add(&bar[XB_XSUB(b.x)], 1u);
;     const unsigned gen = old / nloc;
;     if (old + 1u == (gen + 1u) * nloc) {
;       __builtin_amdgcn_fence(__ATOMIC_RELEASE, "agent");
;       asm volatile("s_waitcnt vmcnt(0)" ::: "memory");
;       const unsigned og = xb_add(&bar[XB_TOP], 1u);
;       const unsigned tg = og / nx;
;       if (og + 1u == (tg + 1u) * nx) xb_add(&bar[XB_TOPGEN], 1u);
;       else XB_SPIN(xb_ld(&bar[XB_TOPGEN]) == tg, bar);
.LBB0_934:
	s_or_b64 exec, exec, s[38:39]
	s_waitcnt vmcnt(0)
	v_readfirstlane_b32 s2, v2
	v_cvt_f32_u32_e32 v2, v0
	v_sub_u32_e32 v3, 0, v0
	v_add_u32_e32 v1, s2, v1
	v_readlane_b32 s2, v251, 30
	v_rcp_iflag_f32_e32 v2, v2
	v_readlane_b32 s3, v251, 31
	s_mov_b64 s[38:39], 0
	v_mul_f32_e32 v2, 0x4f7ffffe, v2
	v_cvt_u32_f32_e32 v2, v2
	v_mul_lo_u32 v3, v3, v2
	v_mul_hi_u32 v3, v2, v3
	v_add_u32_e32 v2, v2, v3
	v_mul_hi_u32 v2, v1, v2
	v_mul_lo_u32 v3, v2, v0
	v_sub_u32_e32 v3, v1, v3
	v_cmp_ge_u32_e32 vcc, v3, v0
	v_add_u32_e32 v4, 1, v2
	v_add_u32_e32 v1, 1, v1
	v_cndmask_b32_e32 v2, v2, v4, vcc
	v_sub_u32_e32 v4, v3, v0
	v_cndmask_b32_e32 v3, v3, v4, vcc
	v_cmp_ge_u32_e32 vcc, v3, v0
	v_add_u32_e32 v3, 1, v2
	s_nop 0
	v_cndmask_b32_e32 v2, v2, v3, vcc
	v_mul_lo_u32 v3, v0, v2
	v_add_u32_e32 v0, v3, v0
	v_mov_b32_e32 v4, v0
	v_cmp_ne_u32_e32 vcc, v1, v0
	v_mov_b64_e32 v[0:1], s[2:3]
	s_and_saveexec_b64 s[2:3], vcc
	s_cbranch_execz .LBB0_946
	v_readlane_b32 s4, v251, 28
	v_readlane_b32 s5, v251, 29
	s_mov_b64 s[40:41], 0
	s_nop 3
	global_load_dword v0, v177, s[4:5] sc1
	s_waitcnt vmcnt(0)
	v_cmp_lt_u32_e32 vcc, v0, v4
	s_and_saveexec_b64 s[38:39], vcc
	s_cbranch_execz .LBB0_945
	s_mov_b32 s11, 1
	s_branch .LBB0_938

; __device__ __forceinline__ unsigned xb_ld(unsigned* p)              { return __hip_atomic_load(p, __ATOMIC_RELAXED, __HIP_MEMORY_SCOPE_AGENT); }
; __device__ __forceinline__ unsigned xb_add(unsigned* p, unsigned v) { return __hip_atomic_fetch_add(p, v, __ATOMIC_RELAXED, __HIP_MEMORY_SCOPE_AGENT); }
; #define XB_SPIN(cond, bar) do { unsigned _sp = 0; while (cond) { __builtin_amdgcn_s_sleep(1); \
;     if ((++_sp & 255u) == 0u) { if (xb_ld(&(bar)[XB_TMO])) break; if (_sp > XB_SPIN_CAP) { atomicAdd(&(bar)[XB_TMO], 1u); break; } } } } while (0)
; __device__ __forceinline__ void xcd_barrier(const XcdBarrier& b) {
;     ...
;       const unsigned og = xb_add(&bar[XB_TOP], 1u);
;       const unsigned tg = og / nx;
;       if (og + 1u == (tg + 1u) * nx) xb_add(&bar[XB_TOPGEN], 1u);
;       else XB_SPIN(xb_ld(&bar[XB_TOPGEN]) == tg, bar);
.LBB0_942:
	v_readlane_b32 s4, v251, 28
	v_readlane_b32 s5, v251, 29
	s_add_i32 s11, s11, 1
	s_mov_b64 s[88:89], -1
	s_nop 2
	global_load_dword v0, v177, s[4:5] sc1
	s_waitcnt vmcnt(0)
	v_cmp_ge_u32_e32 vcc, v0, v4
	s_orn2_b64 s[86:87], vcc, exec
	s_branch .LBB0_937
.LBB0_943:
	s_cmp_lt_u32 s11, 0x2001
	s_mov_b64 s[88:89], 0
	s_cselect_b64 s[90:91], -1, 0
	s_and_b64 vcc, exec, s[90:91]
	s_cbranch_vccz .LBB0_937
	s_branch .LBB0_942

; __device__ __forceinline__ unsigned xb_ld(unsigned* p)              { return __hip_atomic_load(p, __ATOMIC_RELAXED, __HIP_MEMORY_SCOPE_AGENT); }
; __device__ __forceinline__ unsigned xb_add(unsigned* p, unsigned v) { return __hip_atomic_fetch_add(p, v, __ATOMIC_RELAXED, __HIP_MEMORY_SCOPE_AGENT); }
; #define XB_SPIN(cond, bar) do { unsigned _sp = 0; while (cond) { __builtin_amdgcn_s_sleep(1); \
;     if ((++_sp & 255u) == 0u) { if (xb_ld(&(bar)[XB_TMO])) break; if (_sp > XB_SPIN_CAP) { atomicAdd(&(bar)[XB_TMO], 1u); break; } } } } while (0)
; __device__ __forceinline__ void xcd_barrier(const XcdBarrier& b) {
;     ...
;     const unsigned old = xb_add(&bar[XB_XSUB(b.x)], 1u);
;     const unsigned gen = old / nloc;
;     if (old + 1u == (gen + 1u) * nloc) {
;       __builtin_amdgcn_fence(__ATOMIC_RELEASE, "agent");
;       asm volatile("s_waitcnt vmcnt(0)" ::: "memory");
;       const unsigned og = xb_add(&bar[XB_TOP], 1u);
;       const unsigned tg = og / nx;
;       if (og + 1u == (tg + 1u) * nx) xb_add(&bar[XB_TOPGEN], 1u);
;       else XB_SPIN(xb_ld(&bar[XB_TOPGEN]) == tg, bar);
.LBB0_1115:
	s_or_b64 exec, exec, s[40:41]
	s_waitcnt vmcnt(0)
	v_readfirstlane_b32 s2, v2
	v_cvt_f32_u32_e32 v2, v0
	v_sub_u32_e32 v3, 0, v0
	v_add_u32_e32 v1, s2, v1
	v_readlane_b32 s2, v251, 30
	v_rcp_iflag_f32_e32 v2, v2
	v_readlane_b32 s3, v251, 31
	s_mov_b64 s[40:41], 0
	v_mul_f32_e32 v2, 0x4f7ffffe, v2
	v_cvt_u32_f32_e32 v2, v2
	v_mul_lo_u32 v3, v3, v2
	v_mul_hi_u32 v3, v2, v3
	v_add_u32_e32 v2, v2, v3
	v_mul_hi_u32 v2, v1, v2
	v_mul_lo_u32 v3, v2, v0
	v_sub_u32_e32 v3, v1, v3
	v_cmp_ge_u32_e32 vcc, v3, v0
	v_add_u32_e32 v4, 1, v2
	v_add_u32_e32 v1, 1, v1
	v_cndmask_b32_e32 v2, v2, v4, vcc
	v_sub_u32_e32 v4, v3, v0
	v_cndmask_b32_e32 v3, v3, v4, vcc
	v_cmp_ge_u32_e32 vcc, v3, v0
	v_add_u32_e32 v3, 1, v2
	s_nop 0
	v_cndmask_b32_e32 v2, v2, v3, vcc
	v_mul_lo_u32 v3, v0, v2
	v_add_u32_e32 v0, v3, v0
	v_mov_b32_e32 v4, v0
	v_cmp_ne_u32_e32 vcc, v1, v0
	v_mov_b64_e32 v[0:1], s[2:3]
	s_and_saveexec_b64 s[38:39], vcc
	s_cbranch_execz .LBB0_1127
	v_readlane_b32 s2, v251, 28
	v_readlane_b32 s3, v251, 29
	s_mov_b64 s[42:43], 0
	s_nop 3
	global_load_dword v0, v177, s[2:3] sc1
	s_waitcnt vmcnt(0)
	v_cmp_lt_u32_e32 vcc, v0, v4
	s_and_saveexec_b64 s[40:41], vcc
	s_cbranch_execz .LBB0_1126
	s_mov_b32 s2, 1
	s_branch .LBB0_1119

; __device__ __forceinline__ unsigned xb_ld(unsigned* p)              { return __hip_atomic_load(p, __ATOMIC_RELAXED, __HIP_MEMORY_SCOPE_AGENT); }
; __device__ __forceinline__ unsigned xb_add(unsigned* p, unsigned v) { return __hip_atomic_fetch_add(p, v, __ATOMIC_RELAXED, __HIP_MEMORY_SCOPE_AGENT); }
; #define XB_SPIN(cond, bar) do { unsigned _sp = 0; while (cond) { __builtin_amdgcn_s_sleep(1); \
;     if ((++_sp & 255u) == 0u) { if (xb_ld(&(bar)[XB_TMO])) break; if (_sp > XB_SPIN_CAP) { atomicAdd(&(bar)[XB_TMO], 1u); break; } } } } while (0)
; __device__ __forceinline__ void xcd_barrier(const XcdBarrier& b) {
;     ...
;       const unsigned og = xb_add(&bar[XB_TOP], 1u);
;       const unsigned tg = og / nx;
;       if (og + 1u == (tg + 1u) * nx) xb_add(&bar[XB_TOPGEN], 1u);
;       else XB_SPIN(xb_ld(&bar[XB_TOPGEN]) == tg, bar);
.LBB0_1123:
	v_readlane_b32 s4, v251, 28
	v_readlane_b32 s5, v251, 29
	s_add_i32 s2, s2, 1
	s_mov_b64 s[90:91], -1
	s_nop 2
	global_load_dword v0, v177, s[4:5] sc1
	s_waitcnt vmcnt(0)
	v_cmp_ge_u32_e32 vcc, v0, v4
	s_orn2_b64 s[88:89], vcc, exec
	s_branch .LBB0_1118
.LBB0_1124:
	s_cmp_lt_u32 s2, 0x2001
	s_mov_b64 s[90:91], 0
	s_cselect_b64 vcc, -1, 0
	s_and_b64 vcc, exec, vcc
	s_cbranch_vccz .LBB0_1118
	s_branch .LBB0_1123

; __device__ __forceinline__ unsigned xb_ld(unsigned* p)              { return __hip_atomic_load(p, __ATOMIC_RELAXED, __HIP_MEMORY_SCOPE_AGENT); }
; __device__ __forceinline__ unsigned xb_add(unsigned* p, unsigned v) { return __hip_atomic_fetch_add(p, v, __ATOMIC_RELAXED, __HIP_MEMORY_SCOPE_AGENT); }
; #define XB_SPIN(cond, bar) do { unsigned _sp = 0; while (cond) { __builtin_amdgcn_s_sleep(1); \
;     if ((++_sp & 255u) == 0u) { if (xb_ld(&(bar)[XB_TMO])) break; if (_sp > XB_SPIN_CAP) { atomicAdd(&(bar)[XB_TMO], 1u); break; } } } } while (0)
; __device__ __forceinline__ void xcd_barrier(const XcdBarrier& b) {
;     ...
;       const unsigned og = xb_add(&bar[XB_TOP], 1u);
;       const unsigned tg = og / nx;
;       if (og + 1u == (tg + 1u) * nx) xb_add(&bar[XB_TOPGEN], 1u);
;       else XB_SPIN(xb_ld(&bar[XB_TOPGEN]) == tg, bar);
.LBB0_1313:
	v_readlane_b32 s4, v251, 28
	v_readlane_b32 s5, v251, 29
	s_add_i32 s11, s11, 1
	s_mov_b64 s[86:87], -1
	s_nop 2
	global_load_dword v0, v177, s[4:5] sc1
	s_waitcnt vmcnt(0)
	v_cmp_ge_u32_e32 vcc, v0, v4
	s_orn2_b64 s[76:77], vcc, exec
	s_branch .LBB0_1308
.LBB0_1314:
	s_cmp_lt_u32 s11, 0x2001
	s_mov_b64 s[86:87], 0
	s_cselect_b64 s[88:89], -1, 0
	s_and_b64 vcc, exec, s[88:89]
	s_cbranch_vccz .LBB0_1308
	s_branch .LBB0_1313
